# P2b dynamic queue order changed: all diff-attention units first (largest first), then stick-breaking units, then memory units; on top of v58
# baseline (speedup 1.0000x reference)
.LBB0_349:
	v_readlane_b32 s0, v255, 16
	s_waitcnt lgkmcnt(0)
	s_barrier
	v_mov_b32_e32 v0, s0
	ds_read_b32 v0, v0
	s_movk_i32 s0, 0x4ff
	s_waitcnt lgkmcnt(0)
	s_barrier
	v_cmp_lt_u32_e32 vcc, s0, v0
	v_readfirstlane_b32 s16, v0
	s_mov_b64 s[0:1], -1
	s_cbranch_vccnz .LBB0_342
	s_cmpk_gt_u32 s16, 0x3ff
	s_cbranch_scc1 .Lq_remap_done
	s_and_b32 s4, s16, 31
	s_bfe_u32 s5, s16, 0x40005
	s_lshl_b32 s5, s5, 6
	s_or_b32 s4, s4, s5
	s_cmp_lt_u32 s16, 0x200
	s_cselect_b32 s5, 32, 0
	s_or_b32 s16, s4, s5
.Lq_remap_done:
	s_cmpk_gt_u32 s16, 0x3ff
	s_cbranch_scc0 .LBB0_352
	v_readlane_b32 s0, v255, 55
	v_readlane_b32 s1, v255, 56
	v_readlane_b32 s4, v255, 22
	s_add_i32 s4, s4, 2
	s_mul_i32 s4, s4, s80
	v_mov_b32_e32 v0, 0
	s_mov_b32 s5, 0
	s_nop 3
